# SwiGLU->fp8 epilogues (MoE up, dense up) rewritten with packed f32 math and exact power-of-two constant folding; residual epilogues pipelined; diff-attn DMA issue hoisted into MFMA drain
# speedup vs baseline: 1.0068x; 1.0068x over previous
.LBB0_469:
	s_lshl_b32 s6, s6, 1
	v_add_u32_e32 v212, s6, v250
	ds_read_b64_tr_b16 v[208:209], v212 offset:24576
	ds_read_b64_tr_b16 v[210:211], v212 offset:25088
	v_add_f32_e32 v0, v96, v97
	v_add_f32_e32 v0, v98, v0
	v_add_f32_e32 v0, v99, v0
	v_add_f32_e32 v0, v100, v0
	v_add_f32_e32 v0, v101, v0
	v_cvt_pk_bf16_f32 v156, v96, v97
	v_cvt_pk_bf16_f32 v157, v98, v99
	v_mfma_f32_32x32x16_bf16 v[112:127], v[204:207], v[172:175], 0
	ds_read_b64_tr_b16 v[204:205], v212 offset:28672
	ds_read_b64_tr_b16 v[206:207], v212 offset:29184
	v_add_f32_e32 v0, v102, v0
	v_add_f32_e32 v0, v103, v0
	v_add_f32_e32 v0, v104, v0
	v_add_f32_e32 v0, v105, v0
	v_cvt_pk_bf16_f32 v158, v100, v101
	v_cvt_pk_bf16_f32 v159, v102, v103
	v_mfma_f32_32x32x16_bf16 v[128:143], v[200:203], v[172:175], 0
	ds_read_b64_tr_b16 v[10:11], v212 offset:25600
	ds_read_b64_tr_b16 v[12:13], v212 offset:26112
	v_add_f32_e32 v0, v106, v0
	v_add_f32_e32 v0, v107, v0
	v_add_f32_e32 v0, v108, v0
	v_add_f32_e32 v0, v109, v0
	v_cvt_pk_bf16_f32 v152, v104, v105
	v_cvt_pk_bf16_f32 v153, v106, v107
	v_mfma_f32_32x32x16_bf16 v[112:127], v[196:199], v[168:171], v[112:127]
	ds_read_b64_tr_b16 v[6:7], v212 offset:29696
	ds_read_b64_tr_b16 v[8:9], v212 offset:30208
	v_add_f32_e32 v0, v110, v0
	v_add_f32_e32 v0, v111, v0
	v_add_f32_e32 v0, v80, v0
	v_add_f32_e32 v0, v81, v0
	v_cvt_pk_bf16_f32 v154, v108, v109
	v_cvt_pk_bf16_f32 v155, v110, v111
	v_mfma_f32_32x32x16_bf16 v[128:143], v[192:195], v[168:171], v[128:143]
	ds_read_b64_tr_b16 v[2:3], v212 offset:26624
	ds_read_b64_tr_b16 v[4:5], v212 offset:27136
	v_add_f32_e32 v0, v82, v0
	v_add_f32_e32 v0, v83, v0
	v_add_f32_e32 v0, v84, v0
	v_add_f32_e32 v0, v85, v0
	v_cvt_pk_bf16_f32 v148, v80, v81
	v_cvt_pk_bf16_f32 v149, v82, v83
	v_mfma_f32_32x32x16_bf16 v[112:127], v[188:191], v[164:167], v[112:127]
	ds_read_b64_tr_b16 v[188:189], v212 offset:30720
	ds_read_b64_tr_b16 v[190:191], v212 offset:31232
	v_add_f32_e32 v0, v86, v0
	v_add_f32_e32 v0, v87, v0
	v_add_f32_e32 v0, v88, v0
	v_add_f32_e32 v0, v89, v0
	v_cvt_pk_bf16_f32 v150, v84, v85
	v_cvt_pk_bf16_f32 v151, v86, v87
	v_mfma_f32_32x32x16_bf16 v[128:143], v[184:187], v[164:167], v[128:143]
	ds_read_b64_tr_b16 v[192:193], v212 offset:27648
	ds_read_b64_tr_b16 v[194:195], v212 offset:28160
	v_add_f32_e32 v0, v90, v0
	v_add_f32_e32 v0, v91, v0
	v_add_f32_e32 v0, v92, v0
	v_add_f32_e32 v0, v93, v0
	v_cvt_pk_bf16_f32 v144, v88, v89
	v_cvt_pk_bf16_f32 v145, v90, v91
	v_mfma_f32_32x32x16_bf16 v[112:127], v[180:183], v[160:163], v[112:127]
	ds_read_b64_tr_b16 v[196:197], v212 offset:31744
	ds_read_b64_tr_b16 v[198:199], v212 offset:32256
	v_add_f32_e32 v0, v94, v0
	v_add_f32_e32 v0, v95, v0
	v_add_f32_e32 v0, 0, v0
	v_cvt_pk_bf16_f32 v146, v92, v93
	v_cvt_pk_bf16_f32 v147, v94, v95
	v_mfma_f32_32x32x16_bf16 v[128:143], v[176:179], v[160:163], v[128:143]
	s_lshl_b32 s41, s42, 13
	s_add_i32 s7, s48, s77
	s_mov_b32 m0, s7
	s_add_i32 s6, s41, 0x6000
	buffer_load_dwordx4 v247, s[12:15], s6 offen lds
	s_lshl_b32 s7, s40, 1
	s_add_i32 s6, s43, 0x4000
	s_add_i32 s44, s7, s81
	s_mov_b32 m0, s44
	s_nop 0
	buffer_load_dwordx4 v248, s[16:19], s6 offen lds
	s_add_i32 s6, s43, 0x4080
	s_add_i32 s7, s7, s55
	s_mov_b32 m0, s7
	s_nop 0
	buffer_load_dwordx4 v248, s[16:19], s6 offen lds
	v_add_f32_e64 v80, v112, -v228
	v_add_f32_e64 v81, v113, -v228
	v_pk_add_f32 v[14:15], v[128:129], v[228:229] op_sel_hi:[1,0] neg_lo:[0,1] neg_hi:[0,1]
	v_pk_add_f32 v[98:99], v[114:115], v[228:229] op_sel_hi:[1,0] neg_lo:[0,1] neg_hi:[0,1]
	v_pk_add_f32 v[82:83], v[130:131], v[228:229] op_sel_hi:[1,0] neg_lo:[0,1] neg_hi:[0,1]
	v_max_f32_e32 v96, v80, v81
	v_pk_add_f32 v[100:101], v[116:117], v[228:229] op_sel_hi:[1,0] neg_lo:[0,1] neg_hi:[0,1]
	v_pk_add_f32 v[102:103], v[118:119], v[228:229] op_sel_hi:[1,0] neg_lo:[0,1] neg_hi:[0,1]
	v_max3_f32 v97, v98, v99, v15
	v_max3_f32 v96, v96, v14, v82
	v_pk_add_f32 v[84:85], v[132:133], v[228:229] op_sel_hi:[1,0] neg_lo:[0,1] neg_hi:[0,1]
	v_pk_add_f32 v[86:87], v[134:135], v[228:229] op_sel_hi:[1,0] neg_lo:[0,1] neg_hi:[0,1]
	v_max3_f32 v96, v96, v83, v100
	v_max3_f32 v97, v97, v102, v103
	v_pk_add_f32 v[104:105], v[120:121], v[228:229] op_sel_hi:[1,0] neg_lo:[0,1] neg_hi:[0,1]
	v_pk_add_f32 v[106:107], v[122:123], v[228:229] op_sel_hi:[1,0] neg_lo:[0,1] neg_hi:[0,1]
	v_max3_f32 v96, v96, v101, v84
	v_max3_f32 v97, v97, v86, v87
	v_pk_add_f32 v[88:89], v[136:137], v[228:229] op_sel_hi:[1,0] neg_lo:[0,1] neg_hi:[0,1]
	v_pk_add_f32 v[90:91], v[138:139], v[228:229] op_sel_hi:[1,0] neg_lo:[0,1] neg_hi:[0,1]
	v_max3_f32 v96, v96, v85, v104
	v_max3_f32 v97, v97, v106, v107
	v_pk_add_f32 v[108:109], v[124:125], v[228:229] op_sel_hi:[1,0] neg_lo:[0,1] neg_hi:[0,1]
	v_pk_add_f32 v[110:111], v[126:127], v[228:229] op_sel_hi:[1,0] neg_lo:[0,1] neg_hi:[0,1]
	v_max3_f32 v96, v96, v105, v88
	v_max3_f32 v97, v97, v90, v91
	v_pk_add_f32 v[92:93], v[140:141], v[228:229] op_sel_hi:[1,0] neg_lo:[0,1] neg_hi:[0,1]
	v_pk_add_f32 v[94:95], v[142:143], v[228:229] op_sel_hi:[1,0] neg_lo:[0,1] neg_hi:[0,1]
	v_max3_f32 v96, v96, v89, v108
	v_max3_f32 v97, v97, v110, v111
	v_max3_f32 v96, v96, v109, v92
	v_max3_f32 v97, v97, v94, v95
	v_max3_f32 v96, v96, v93, v97
	v_add_f32_e32 v0, v251, v0
	v_cmp_lt_f32_e32 vcc, s83, v96
	s_cmp_lg_u64 vcc, 0
	s_cselect_b64 s[6:7], -1, 0
	s_cbranch_vccnz .LBB0_477

.LBB0_472:
	s_add_i32 s6, s40, 0x2000
	s_cmpk_lg_i32 s40, 0x4000
	s_cselect_b32 s91, s6, 0
	s_lshl_b32 s6, s48, 1
	v_add_u32_e32 v14, s6, v250
	ds_read_b64_tr_b16 v[192:193], v14 offset:24576
	ds_read_b64_tr_b16 v[194:195], v14 offset:25088
	v_add_f32_e32 v15, v96, v97
	v_add_f32_e32 v15, v98, v15
	v_add_f32_e32 v15, v99, v15
	v_add_f32_e32 v15, v100, v15
	v_add_f32_e32 v15, v101, v15
	v_cvt_pk_bf16_f32 v156, v96, v97
	v_cvt_pk_bf16_f32 v157, v98, v99
	v_mfma_f32_32x32x16_bf16 v[112:127], v[112:115], v[172:175], 0
	ds_read_b64_tr_b16 v[196:197], v14 offset:28672
	ds_read_b64_tr_b16 v[198:199], v14 offset:29184
	v_add_f32_e32 v15, v102, v15
	v_add_f32_e32 v15, v103, v15
	v_add_f32_e32 v15, v104, v15
	v_add_f32_e32 v15, v105, v15
	v_cvt_pk_bf16_f32 v158, v100, v101
	v_cvt_pk_bf16_f32 v159, v102, v103
	v_mfma_f32_32x32x16_bf16 v[128:143], v[128:131], v[172:175], 0
	ds_read_b64_tr_b16 v[188:189], v14 offset:25600
	ds_read_b64_tr_b16 v[190:191], v14 offset:26112
	v_add_f32_e32 v15, v106, v15
	v_add_f32_e32 v15, v107, v15
	v_add_f32_e32 v15, v108, v15
	v_add_f32_e32 v15, v109, v15
	v_cvt_pk_bf16_f32 v152, v104, v105
	v_cvt_pk_bf16_f32 v153, v106, v107
	v_mfma_f32_32x32x16_bf16 v[112:127], v[184:187], v[168:171], v[112:127]
	ds_read_b64_tr_b16 v[184:185], v14 offset:29696
	ds_read_b64_tr_b16 v[186:187], v14 offset:30208
	v_add_f32_e32 v15, v110, v15
	v_add_f32_e32 v15, v111, v15
	v_add_f32_e32 v15, v80, v15
	v_add_f32_e32 v15, v81, v15
	v_cvt_pk_bf16_f32 v154, v108, v109
	v_cvt_pk_bf16_f32 v155, v110, v111
	v_mfma_f32_32x32x16_bf16 v[128:143], v[176:179], v[168:171], v[128:143]
	ds_read_b64_tr_b16 v[176:177], v14 offset:26624
	ds_read_b64_tr_b16 v[178:179], v14 offset:27136
	v_add_f32_e32 v15, v82, v15
	v_add_f32_e32 v15, v83, v15
	v_add_f32_e32 v15, v84, v15
	v_add_f32_e32 v15, v85, v15
	v_cvt_pk_bf16_f32 v148, v80, v81
	v_cvt_pk_bf16_f32 v149, v82, v83
	v_mfma_f32_32x32x16_bf16 v[112:127], v[180:183], v[164:167], v[112:127]
	ds_read_b64_tr_b16 v[208:209], v14 offset:30720
	ds_read_b64_tr_b16 v[210:211], v14 offset:31232
	v_add_f32_e32 v15, v86, v15
	v_add_f32_e32 v15, v87, v15
	v_add_f32_e32 v15, v88, v15
	v_add_f32_e32 v15, v89, v15
	v_cvt_pk_bf16_f32 v150, v84, v85
	v_cvt_pk_bf16_f32 v151, v86, v87
	v_mfma_f32_32x32x16_bf16 v[128:143], v[6:9], v[164:167], v[128:143]
	ds_read_b64_tr_b16 v[6:7], v14 offset:27648
	ds_read_b64_tr_b16 v[8:9], v14 offset:28160
	v_add_f32_e32 v15, v90, v15
	v_add_f32_e32 v15, v91, v15
	v_add_f32_e32 v15, v92, v15
	v_add_f32_e32 v15, v93, v15
	v_cvt_pk_bf16_f32 v144, v88, v89
	v_cvt_pk_bf16_f32 v145, v90, v91
	v_mfma_f32_32x32x16_bf16 v[112:127], v[10:13], v[160:163], v[112:127]
	ds_read_b64_tr_b16 v[10:11], v14 offset:31744
	ds_read_b64_tr_b16 v[12:13], v14 offset:32256
	v_add_f32_e32 v15, v94, v15
	v_add_f32_e32 v15, v95, v15
	v_add_f32_e32 v15, 0, v15
	v_cvt_pk_bf16_f32 v146, v92, v93
	v_cvt_pk_bf16_f32 v147, v94, v95
	v_mfma_f32_32x32x16_bf16 v[128:143], v[2:5], v[160:163], v[128:143]
	s_add_i32 s6, s40, s77
	s_mov_b32 m0, s6
	s_add_i32 s41, s41, 0x8000
	buffer_load_dwordx4 v247, s[12:15], s41 offen lds
	s_lshl_b32 s6, s91, 1
	s_add_i32 s48, s43, 0x8000
	s_add_i32 s7, s6, s81
	s_mov_b32 m0, s7
	s_nop 0
	buffer_load_dwordx4 v248, s[16:19], s48 offen lds
	s_add_i32 s7, s43, 0x8080
	s_add_i32 s6, s6, s55
	s_mov_b32 m0, s6
	s_nop 0
	buffer_load_dwordx4 v248, s[16:19], s7 offen lds
	v_add_f32_e64 v4, v112, -v228
	v_add_f32_e64 v5, v113, -v228
	v_pk_add_f32 v[2:3], v[128:129], v[228:229] op_sel_hi:[1,0] neg_lo:[0,1] neg_hi:[0,1]
	v_pk_add_f32 v[98:99], v[114:115], v[228:229] op_sel_hi:[1,0] neg_lo:[0,1] neg_hi:[0,1]
	v_pk_add_f32 v[82:83], v[130:131], v[228:229] op_sel_hi:[1,0] neg_lo:[0,1] neg_hi:[0,1]
	v_max_f32_e32 v80, v4, v5
	v_pk_add_f32 v[100:101], v[116:117], v[228:229] op_sel_hi:[1,0] neg_lo:[0,1] neg_hi:[0,1]
	v_pk_add_f32 v[102:103], v[118:119], v[228:229] op_sel_hi:[1,0] neg_lo:[0,1] neg_hi:[0,1]
	v_max3_f32 v81, v98, v99, v3
	v_max3_f32 v80, v80, v2, v82
	v_pk_add_f32 v[84:85], v[132:133], v[228:229] op_sel_hi:[1,0] neg_lo:[0,1] neg_hi:[0,1]
	v_pk_add_f32 v[86:87], v[134:135], v[228:229] op_sel_hi:[1,0] neg_lo:[0,1] neg_hi:[0,1]
	v_max3_f32 v80, v80, v83, v100
	v_max3_f32 v81, v81, v102, v103
	v_pk_add_f32 v[104:105], v[120:121], v[228:229] op_sel_hi:[1,0] neg_lo:[0,1] neg_hi:[0,1]
	v_pk_add_f32 v[106:107], v[122:123], v[228:229] op_sel_hi:[1,0] neg_lo:[0,1] neg_hi:[0,1]
	v_max3_f32 v80, v80, v101, v84
	v_max3_f32 v81, v81, v86, v87
	v_pk_add_f32 v[88:89], v[136:137], v[228:229] op_sel_hi:[1,0] neg_lo:[0,1] neg_hi:[0,1]
	v_pk_add_f32 v[90:91], v[138:139], v[228:229] op_sel_hi:[1,0] neg_lo:[0,1] neg_hi:[0,1]
	v_max3_f32 v80, v80, v85, v104
	v_max3_f32 v81, v81, v106, v107
	v_pk_add_f32 v[108:109], v[124:125], v[228:229] op_sel_hi:[1,0] neg_lo:[0,1] neg_hi:[0,1]
	v_pk_add_f32 v[110:111], v[126:127], v[228:229] op_sel_hi:[1,0] neg_lo:[0,1] neg_hi:[0,1]
	v_max3_f32 v80, v80, v105, v88
	v_max3_f32 v81, v81, v90, v91
	v_pk_add_f32 v[92:93], v[140:141], v[228:229] op_sel_hi:[1,0] neg_lo:[0,1] neg_hi:[0,1]
	v_pk_add_f32 v[94:95], v[142:143], v[228:229] op_sel_hi:[1,0] neg_lo:[0,1] neg_hi:[0,1]
	v_max3_f32 v80, v80, v89, v108
	v_max3_f32 v81, v81, v110, v111
	v_max3_f32 v80, v80, v109, v92
	v_max3_f32 v81, v81, v94, v95
	v_add_f32_e32 v251, v0, v15
	v_max3_f32 v0, v80, v93, v81
	v_cmp_lt_f32_e32 vcc, s83, v0
	s_cmp_lg_u64 vcc, 0
	s_cselect_b64 s[6:7], -1, 0
	s_cbranch_vccnz .LBB0_480

.LBB0_477:
	v_mov_b32_e32 v97, v96
	s_nop 1
	v_permlane32_swap_b32_e32 v96, v97
	v_max_f32_e32 v97, v97, v97
	v_max_f32_e32 v96, v96, v96
	v_max_f32_e32 v96, v96, v97
	v_max_f32_e32 v96, v96, v96
	v_max_f32_e32 v97, 0, v96
	v_exp_f32_e64 v96, -v97
	s_and_saveexec_b64 s[44:45], s[4:5]
	ds_write_b32 v243, v96
	s_or_b64 exec, exec, s[44:45]
	v_sub_f32_e32 v80, v80, v97
	v_sub_f32_e32 v81, v81, v97
	v_sub_f32_e32 v98, v98, v97
	v_sub_f32_e32 v99, v99, v97
	v_sub_f32_e32 v100, v100, v97
	v_sub_f32_e32 v101, v101, v97
	v_sub_f32_e32 v102, v102, v97
	v_sub_f32_e32 v103, v103, v97
	v_sub_f32_e32 v104, v104, v97
	v_sub_f32_e32 v105, v105, v97
	v_sub_f32_e32 v106, v106, v97
	v_sub_f32_e32 v107, v107, v97
	v_sub_f32_e32 v108, v108, v97
	v_sub_f32_e32 v109, v109, v97
	v_sub_f32_e32 v110, v110, v97
	v_sub_f32_e32 v111, v111, v97
	v_sub_f32_e32 v14, v14, v97
	v_sub_f32_e32 v15, v15, v97
	v_sub_f32_e32 v82, v82, v97
	v_sub_f32_e32 v83, v83, v97
	v_sub_f32_e32 v84, v84, v97
	v_sub_f32_e32 v85, v85, v97
	v_sub_f32_e32 v86, v86, v97
	v_sub_f32_e32 v87, v87, v97
	v_sub_f32_e32 v88, v88, v97
	v_sub_f32_e32 v89, v89, v97
	v_sub_f32_e32 v90, v90, v97
	v_sub_f32_e32 v91, v91, v97
	v_sub_f32_e32 v92, v92, v97
	v_sub_f32_e32 v93, v93, v97
	v_sub_f32_e32 v94, v94, v97
	v_sub_f32_e32 v95, v95, v97
	v_add_f32_e32 v228, v228, v97
	v_mul_f32_e32 v0, v0, v96
	s_branch .LBB0_470
.LBB0_480:
	v_mov_b32_e32 v15, v0
	s_nop 1
	v_permlane32_swap_b32_e32 v0, v15
	v_max_f32_e32 v15, v15, v15
	v_max_f32_e32 v0, v0, v0
	v_max_f32_e32 v0, v0, v15
	v_max_f32_e32 v0, v0, v0
	v_max_f32_e32 v15, 0, v0
	v_exp_f32_e64 v0, -v15
	s_and_saveexec_b64 s[44:45], s[4:5]
	ds_write_b32 v243, v0
	s_or_b64 exec, exec, s[44:45]
	v_sub_f32_e32 v4, v4, v15
	v_sub_f32_e32 v5, v5, v15
	v_sub_f32_e32 v98, v98, v15
	v_sub_f32_e32 v99, v99, v15
	v_sub_f32_e32 v100, v100, v15
	v_sub_f32_e32 v101, v101, v15
	v_sub_f32_e32 v102, v102, v15
	v_sub_f32_e32 v103, v103, v15
	v_sub_f32_e32 v104, v104, v15
	v_sub_f32_e32 v105, v105, v15
	v_sub_f32_e32 v106, v106, v15
	v_sub_f32_e32 v107, v107, v15
	v_sub_f32_e32 v108, v108, v15
	v_sub_f32_e32 v109, v109, v15
	v_sub_f32_e32 v110, v110, v15
	v_sub_f32_e32 v111, v111, v15
	v_sub_f32_e32 v2, v2, v15
	v_sub_f32_e32 v3, v3, v15
	v_sub_f32_e32 v82, v82, v15
	v_sub_f32_e32 v83, v83, v15
	v_sub_f32_e32 v84, v84, v15
	v_sub_f32_e32 v85, v85, v15
	v_sub_f32_e32 v86, v86, v15
	v_sub_f32_e32 v87, v87, v15
	v_sub_f32_e32 v88, v88, v15
	v_sub_f32_e32 v89, v89, v15
	v_sub_f32_e32 v90, v90, v15
	v_sub_f32_e32 v91, v91, v15
	v_sub_f32_e32 v92, v92, v15
	v_sub_f32_e32 v93, v93, v15
	v_sub_f32_e32 v94, v94, v15
	v_sub_f32_e32 v95, v95, v15
	v_add_f32_e32 v228, v228, v15
	v_mul_f32_e32 v251, v251, v0
	s_branch .LBB0_473

; __device__ __forceinline__ float sigm(float x) { return __builtin_amdgcn_rcpf(1.f + __builtin_amdgcn_exp2f(-1.4426950408889634f * x)); }
;     __device__ __forceinline__ void operator()(const f32x4 (&acc)[2][2][4][2], const Unit& u, int wr, int wc, int fr, int fq) const {
;         const int pnl = u.pn % nper; const int row0 = u.pm * BM + wr * 64 + fr, col0 = pnl * HALF + wc * 32 + 8 * fq;
; #pragma unroll
;         for (int ai = 0; ai < 2; ++ai)
; #pragma unroll
;             for (int m = 0; m < 4; ++m) { const f32x4 g0 = acc[ai][0][m][0] * isc, g1 = acc[ai][0][m][1] * isc, u0 = acc[ai][1][m][0] * isc, u1 = acc[ai][1][m][1] * isc; float r[8];
; #pragma unroll
;                 for (int i = 0; i < 4; ++i) { r[i] = g0[i] * sigm(g0[i]) * u0[i] * osc; r[4 + i] = g1[i] * sigm(g1[i]) * u1[i] * osc; }
;                 int w0 = 0, w1 = 0; w0 = __builtin_amdgcn_cvt_pk_fp8_f32(r[0], r[1], w0, false); w0 = __builtin_amdgcn_cvt_pk_fp8_f32(r[2], r[3], w0, true);
;                 w1 = __builtin_amdgcn_cvt_pk_fp8_f32(r[4], r[5], w1, false); w1 = __builtin_amdgcn_cvt_pk_fp8_f32(r[6], r[7], w1, true);
;                 typedef unsigned u32x2 __attribute__((ext_vector_type(2)));
;                 *(u32x2*)(O + (size_t)(row0 + ai * HALF + m * 16) * ldo + col0) = (u32x2){(unsigned)w0, (unsigned)w1}; }
;     }
.LBB0_906:
	s_mov_b32 s18, s60
	s_lshl_b32 s18, s18, 7
	s_lshl_b32 s19, s59, 8
	s_add_i32 s19, s19, s71
	v_mbcnt_lo_u32_b32 v145, -1, 0
	v_mbcnt_hi_u32_b32 v145, -1, v145
	v_mov_b32_e32 v146, 0xbcb8aa3b
	v_and_or_b32 v143, v145, 15, s19
	v_lshrrev_b32_e32 v145, 1, v145
	v_mov_b32_e32 v147, 0xbcb8aa3b
	v_and_or_b32 v145, v145, 24, s18
	v_or_b32_e32 v145, s75, v145
	v_mov_b32_e32 v148, 0x3b800000
	v_mov_b32_e32 v149, 0x3b800000
	v_mad_u32_u24 v144, v143, s54, v145
	v_mov_b32_e32 v150, 1.0
	v_mov_b32_e32 v151, 1.0
	s_andn2_b64 vcc, exec, s[10:11]
	s_mov_b64 s[10:11], -1
	v_pk_mul_f32 v[152:153], v[124:125], v[146:147]
	v_pk_mul_f32 v[154:155], v[126:127], v[146:147]
	v_pk_mul_f32 v[156:157], v[120:121], v[146:147]
	v_pk_mul_f32 v[158:159], v[122:123], v[146:147]
	v_exp_f32_e32 v152, v152
	v_exp_f32_e32 v153, v153
	v_exp_f32_e32 v154, v154
	v_exp_f32_e32 v155, v155
	v_exp_f32_e32 v156, v156
	v_exp_f32_e32 v157, v157
	v_exp_f32_e32 v158, v158
	v_exp_f32_e32 v159, v159
	v_pk_add_f32 v[152:153], v[152:153], v[150:151]
	v_pk_add_f32 v[154:155], v[154:155], v[150:151]
	v_pk_add_f32 v[156:157], v[156:157], v[150:151]
	v_pk_add_f32 v[158:159], v[158:159], v[150:151]
	v_rcp_f32_e32 v152, v152
	v_rcp_f32_e32 v153, v153
	v_rcp_f32_e32 v154, v154
	v_rcp_f32_e32 v155, v155
	v_rcp_f32_e32 v156, v156
	v_rcp_f32_e32 v157, v157
	v_rcp_f32_e32 v158, v158
	v_rcp_f32_e32 v159, v159
	v_pk_mul_f32 v[124:125], v[124:125], v[152:153]
	v_pk_mul_f32 v[126:127], v[126:127], v[154:155]
	v_pk_mul_f32 v[120:121], v[120:121], v[156:157]
	v_pk_mul_f32 v[122:123], v[122:123], v[158:159]
	v_pk_mul_f32 v[124:125], v[124:125], v[116:117]
	v_pk_mul_f32 v[126:127], v[126:127], v[118:119]
	v_pk_mul_f32 v[120:121], v[120:121], v[112:113]
	v_pk_mul_f32 v[122:123], v[122:123], v[114:115]
	v_pk_mul_f32 v[124:125], v[124:125], v[148:149]
	v_pk_mul_f32 v[126:127], v[126:127], v[148:149]
	v_pk_mul_f32 v[120:121], v[120:121], v[148:149]
	v_pk_mul_f32 v[122:123], v[122:123], v[148:149]
	v_cvt_pk_fp8_f32 v168, v124, v125
	v_cvt_pk_fp8_f32 v169, v120, v121
	v_cvt_pk_fp8_f32 v168, v126, v127 op_sel:[0,0,1]
	v_cvt_pk_fp8_f32 v169, v122, v123 op_sel:[0,0,1]
	s_nop 0
	global_store_dwordx2 v144, v[168:169], s[22:23]
	v_add_u32_e32 v144, 0xb000, v144
	v_pk_mul_f32 v[160:161], v[108:109], v[146:147]
	v_pk_mul_f32 v[162:163], v[110:111], v[146:147]
	v_pk_mul_f32 v[164:165], v[104:105], v[146:147]
	v_pk_mul_f32 v[166:167], v[106:107], v[146:147]
	v_exp_f32_e32 v160, v160
	v_exp_f32_e32 v161, v161
	v_exp_f32_e32 v162, v162
	v_exp_f32_e32 v163, v163
	v_exp_f32_e32 v164, v164
	v_exp_f32_e32 v165, v165
	v_exp_f32_e32 v166, v166
	v_exp_f32_e32 v167, v167
	v_pk_add_f32 v[160:161], v[160:161], v[150:151]
	v_pk_add_f32 v[162:163], v[162:163], v[150:151]
	v_pk_add_f32 v[164:165], v[164:165], v[150:151]
	v_pk_add_f32 v[166:167], v[166:167], v[150:151]
	v_rcp_f32_e32 v160, v160
	v_rcp_f32_e32 v161, v161
	v_rcp_f32_e32 v162, v162
	v_rcp_f32_e32 v163, v163
	v_rcp_f32_e32 v164, v164
	v_rcp_f32_e32 v165, v165
	v_rcp_f32_e32 v166, v166
	v_rcp_f32_e32 v167, v167
	v_pk_mul_f32 v[108:109], v[108:109], v[160:161]
	v_pk_mul_f32 v[110:111], v[110:111], v[162:163]
	v_pk_mul_f32 v[104:105], v[104:105], v[164:165]
	v_pk_mul_f32 v[106:107], v[106:107], v[166:167]
	v_pk_mul_f32 v[108:109], v[108:109], v[100:101]
	v_pk_mul_f32 v[110:111], v[110:111], v[102:103]
	v_pk_mul_f32 v[104:105], v[104:105], v[96:97]
	v_pk_mul_f32 v[106:107], v[106:107], v[98:99]
	v_pk_mul_f32 v[108:109], v[108:109], v[148:149]
	v_pk_mul_f32 v[110:111], v[110:111], v[148:149]
	v_pk_mul_f32 v[104:105], v[104:105], v[148:149]
	v_pk_mul_f32 v[106:107], v[106:107], v[148:149]
	v_cvt_pk_fp8_f32 v170, v108, v109
	v_cvt_pk_fp8_f32 v171, v104, v105
	v_cvt_pk_fp8_f32 v170, v110, v111 op_sel:[0,0,1]
	v_cvt_pk_fp8_f32 v171, v106, v107 op_sel:[0,0,1]
	s_nop 0
	global_store_dwordx2 v144, v[170:171], s[22:23]
	v_add_u32_e32 v144, 0xb000, v144
	v_pk_mul_f32 v[152:153], v[92:93], v[146:147]
	v_pk_mul_f32 v[154:155], v[94:95], v[146:147]
	v_pk_mul_f32 v[156:157], v[88:89], v[146:147]
	v_pk_mul_f32 v[158:159], v[90:91], v[146:147]
	v_exp_f32_e32 v152, v152
	v_exp_f32_e32 v153, v153
	v_exp_f32_e32 v154, v154
	v_exp_f32_e32 v155, v155
	v_exp_f32_e32 v156, v156
	v_exp_f32_e32 v157, v157
	v_exp_f32_e32 v158, v158
	v_exp_f32_e32 v159, v159
	v_pk_add_f32 v[152:153], v[152:153], v[150:151]
	v_pk_add_f32 v[154:155], v[154:155], v[150:151]
	v_pk_add_f32 v[156:157], v[156:157], v[150:151]
	v_pk_add_f32 v[158:159], v[158:159], v[150:151]
	v_rcp_f32_e32 v152, v152
	v_rcp_f32_e32 v153, v153
	v_rcp_f32_e32 v154, v154
	v_rcp_f32_e32 v155, v155
	v_rcp_f32_e32 v156, v156
	v_rcp_f32_e32 v157, v157
	v_rcp_f32_e32 v158, v158
	v_rcp_f32_e32 v159, v159
	v_pk_mul_f32 v[92:93], v[92:93], v[152:153]
	v_pk_mul_f32 v[94:95], v[94:95], v[154:155]
	v_pk_mul_f32 v[88:89], v[88:89], v[156:157]
	v_pk_mul_f32 v[90:91], v[90:91], v[158:159]
	v_pk_mul_f32 v[92:93], v[92:93], v[84:85]
	v_pk_mul_f32 v[94:95], v[94:95], v[86:87]
	v_pk_mul_f32 v[88:89], v[88:89], v[80:81]
	v_pk_mul_f32 v[90:91], v[90:91], v[82:83]
	v_pk_mul_f32 v[92:93], v[92:93], v[148:149]
	v_pk_mul_f32 v[94:95], v[94:95], v[148:149]
	v_pk_mul_f32 v[88:89], v[88:89], v[148:149]
	v_pk_mul_f32 v[90:91], v[90:91], v[148:149]
	v_cvt_pk_fp8_f32 v168, v92, v93
	v_cvt_pk_fp8_f32 v169, v88, v89
	v_cvt_pk_fp8_f32 v168, v94, v95 op_sel:[0,0,1]
	v_cvt_pk_fp8_f32 v169, v90, v91 op_sel:[0,0,1]
	s_nop 0
	global_store_dwordx2 v144, v[168:169], s[22:23]
	v_add_u32_e32 v144, 0xb000, v144
	v_pk_mul_f32 v[160:161], v[76:77], v[146:147]
	v_pk_mul_f32 v[162:163], v[78:79], v[146:147]
	v_pk_mul_f32 v[164:165], v[72:73], v[146:147]
	v_pk_mul_f32 v[166:167], v[74:75], v[146:147]
; __device__ __forceinline__ float sigm(float x) { return __builtin_amdgcn_rcpf(1.f + __builtin_amdgcn_exp2f(-1.4426950408889634f * x)); }
;     __device__ __forceinline__ void operator()(const f32x4 (&acc)[2][2][4][2], const Unit& u, int wr, int wc, int fr, int fq) const {
;     ...
;         for (int ai = 0; ai < 2; ++ai)
; #pragma unroll
;             for (int m = 0; m < 4; ++m) { const f32x4 g0 = acc[ai][0][m][0] * isc, g1 = acc[ai][0][m][1] * isc, u0 = acc[ai][1][m][0] * isc, u1 = acc[ai][1][m][1] * isc; float r[8];
; #pragma unroll
;                 for (int i = 0; i < 4; ++i) { r[i] = g0[i] * sigm(g0[i]) * u0[i] * osc; r[4 + i] = g1[i] * sigm(g1[i]) * u1[i] * osc; }
;                 int w0 = 0, w1 = 0; w0 = __builtin_amdgcn_cvt_pk_fp8_f32(r[0], r[1], w0, false); w0 = __builtin_amdgcn_cvt_pk_fp8_f32(r[2], r[3], w0, true);
;                 w1 = __builtin_amdgcn_cvt_pk_fp8_f32(r[4], r[5], w1, false); w1 = __builtin_amdgcn_cvt_pk_fp8_f32(r[6], r[7], w1, true);
;                 typedef unsigned u32x2 __attribute__((ext_vector_type(2)));
;                 *(u32x2*)(O + (size_t)(row0 + ai * HALF + m * 16) * ldo + col0) = (u32x2){(unsigned)w0, (unsigned)w1}; }
	v_exp_f32_e32 v160, v160
	v_exp_f32_e32 v161, v161
	v_exp_f32_e32 v162, v162
	v_exp_f32_e32 v163, v163
	v_exp_f32_e32 v164, v164
	v_exp_f32_e32 v165, v165
	v_exp_f32_e32 v166, v166
	v_exp_f32_e32 v167, v167
	v_pk_add_f32 v[160:161], v[160:161], v[150:151]
	v_pk_add_f32 v[162:163], v[162:163], v[150:151]
	v_pk_add_f32 v[164:165], v[164:165], v[150:151]
	v_pk_add_f32 v[166:167], v[166:167], v[150:151]
	v_rcp_f32_e32 v160, v160
	v_rcp_f32_e32 v161, v161
	v_rcp_f32_e32 v162, v162
	v_rcp_f32_e32 v163, v163
	v_rcp_f32_e32 v164, v164
	v_rcp_f32_e32 v165, v165
	v_rcp_f32_e32 v166, v166
	v_rcp_f32_e32 v167, v167
	v_pk_mul_f32 v[76:77], v[76:77], v[160:161]
	v_pk_mul_f32 v[78:79], v[78:79], v[162:163]
	v_pk_mul_f32 v[72:73], v[72:73], v[164:165]
	v_pk_mul_f32 v[74:75], v[74:75], v[166:167]
	v_pk_mul_f32 v[76:77], v[76:77], v[68:69]
	v_pk_mul_f32 v[78:79], v[78:79], v[70:71]
	v_pk_mul_f32 v[72:73], v[72:73], v[64:65]
	v_pk_mul_f32 v[74:75], v[74:75], v[66:67]
	v_pk_mul_f32 v[76:77], v[76:77], v[148:149]
	v_pk_mul_f32 v[78:79], v[78:79], v[148:149]
	v_pk_mul_f32 v[72:73], v[72:73], v[148:149]
	v_pk_mul_f32 v[74:75], v[74:75], v[148:149]
	v_cvt_pk_fp8_f32 v170, v76, v77
	v_cvt_pk_fp8_f32 v171, v72, v73
	v_cvt_pk_fp8_f32 v170, v78, v79 op_sel:[0,0,1]
	v_cvt_pk_fp8_f32 v171, v74, v75 op_sel:[0,0,1]
	s_nop 0
	global_store_dwordx2 v144, v[170:171], s[22:23]
	v_add_u32_e32 v144, 0x37000, v144
	v_pk_mul_f32 v[152:153], v[60:61], v[146:147]
	v_pk_mul_f32 v[154:155], v[62:63], v[146:147]
	v_pk_mul_f32 v[156:157], v[56:57], v[146:147]
	v_pk_mul_f32 v[158:159], v[58:59], v[146:147]
	v_exp_f32_e32 v152, v152
	v_exp_f32_e32 v153, v153
	v_exp_f32_e32 v154, v154
	v_exp_f32_e32 v155, v155
	v_exp_f32_e32 v156, v156
	v_exp_f32_e32 v157, v157
	v_exp_f32_e32 v158, v158
	v_exp_f32_e32 v159, v159
	v_pk_add_f32 v[152:153], v[152:153], v[150:151]
	v_pk_add_f32 v[154:155], v[154:155], v[150:151]
	v_pk_add_f32 v[156:157], v[156:157], v[150:151]
	v_pk_add_f32 v[158:159], v[158:159], v[150:151]
	v_rcp_f32_e32 v152, v152
	v_rcp_f32_e32 v153, v153
	v_rcp_f32_e32 v154, v154
	v_rcp_f32_e32 v155, v155
	v_rcp_f32_e32 v156, v156
	v_rcp_f32_e32 v157, v157
	v_rcp_f32_e32 v158, v158
	v_rcp_f32_e32 v159, v159
	v_pk_mul_f32 v[60:61], v[60:61], v[152:153]
	v_pk_mul_f32 v[62:63], v[62:63], v[154:155]
	v_pk_mul_f32 v[56:57], v[56:57], v[156:157]
	v_pk_mul_f32 v[58:59], v[58:59], v[158:159]
	v_pk_mul_f32 v[60:61], v[60:61], v[52:53]
	v_pk_mul_f32 v[62:63], v[62:63], v[54:55]
	v_pk_mul_f32 v[56:57], v[56:57], v[48:49]
	v_pk_mul_f32 v[58:59], v[58:59], v[50:51]
	v_pk_mul_f32 v[60:61], v[60:61], v[148:149]
	v_pk_mul_f32 v[62:63], v[62:63], v[148:149]
	v_pk_mul_f32 v[56:57], v[56:57], v[148:149]
	v_pk_mul_f32 v[58:59], v[58:59], v[148:149]
	v_cvt_pk_fp8_f32 v168, v60, v61
	v_cvt_pk_fp8_f32 v169, v56, v57
	v_cvt_pk_fp8_f32 v168, v62, v63 op_sel:[0,0,1]
	v_cvt_pk_fp8_f32 v169, v58, v59 op_sel:[0,0,1]
	s_nop 0
	global_store_dwordx2 v144, v[168:169], s[22:23]
	v_add_u32_e32 v144, 0xb000, v144
	v_pk_mul_f32 v[160:161], v[44:45], v[146:147]
	v_pk_mul_f32 v[162:163], v[46:47], v[146:147]
	v_pk_mul_f32 v[164:165], v[40:41], v[146:147]
	v_pk_mul_f32 v[166:167], v[42:43], v[146:147]
	v_exp_f32_e32 v160, v160
	v_exp_f32_e32 v161, v161
	v_exp_f32_e32 v162, v162
	v_exp_f32_e32 v163, v163
	v_exp_f32_e32 v164, v164
	v_exp_f32_e32 v165, v165
	v_exp_f32_e32 v166, v166
	v_exp_f32_e32 v167, v167
	v_pk_add_f32 v[160:161], v[160:161], v[150:151]
	v_pk_add_f32 v[162:163], v[162:163], v[150:151]
	v_pk_add_f32 v[164:165], v[164:165], v[150:151]
	v_pk_add_f32 v[166:167], v[166:167], v[150:151]
	v_rcp_f32_e32 v160, v160
	v_rcp_f32_e32 v161, v161
	v_rcp_f32_e32 v162, v162
	v_rcp_f32_e32 v163, v163
	v_rcp_f32_e32 v164, v164
	v_rcp_f32_e32 v165, v165
	v_rcp_f32_e32 v166, v166
	v_rcp_f32_e32 v167, v167
	v_pk_mul_f32 v[44:45], v[44:45], v[160:161]
	v_pk_mul_f32 v[46:47], v[46:47], v[162:163]
	v_pk_mul_f32 v[40:41], v[40:41], v[164:165]
; __device__ __forceinline__ float sigm(float x) { return __builtin_amdgcn_rcpf(1.f + __builtin_amdgcn_exp2f(-1.4426950408889634f * x)); }
;     __device__ __forceinline__ void operator()(const f32x4 (&acc)[2][2][4][2], const Unit& u, int wr, int wc, int fr, int fq) const {
;     ...
;         for (int ai = 0; ai < 2; ++ai)
; #pragma unroll
;             for (int m = 0; m < 4; ++m) { const f32x4 g0 = acc[ai][0][m][0] * isc, g1 = acc[ai][0][m][1] * isc, u0 = acc[ai][1][m][0] * isc, u1 = acc[ai][1][m][1] * isc; float r[8];
; #pragma unroll
;                 for (int i = 0; i < 4; ++i) { r[i] = g0[i] * sigm(g0[i]) * u0[i] * osc; r[4 + i] = g1[i] * sigm(g1[i]) * u1[i] * osc; }
;                 int w0 = 0, w1 = 0; w0 = __builtin_amdgcn_cvt_pk_fp8_f32(r[0], r[1], w0, false); w0 = __builtin_amdgcn_cvt_pk_fp8_f32(r[2], r[3], w0, true);
;                 w1 = __builtin_amdgcn_cvt_pk_fp8_f32(r[4], r[5], w1, false); w1 = __builtin_amdgcn_cvt_pk_fp8_f32(r[6], r[7], w1, true);
;                 typedef unsigned u32x2 __attribute__((ext_vector_type(2)));
;                 *(u32x2*)(O + (size_t)(row0 + ai * HALF + m * 16) * ldo + col0) = (u32x2){(unsigned)w0, (unsigned)w1}; }
	v_pk_mul_f32 v[42:43], v[42:43], v[166:167]
	v_pk_mul_f32 v[44:45], v[44:45], v[36:37]
	v_pk_mul_f32 v[46:47], v[46:47], v[38:39]
	v_pk_mul_f32 v[40:41], v[40:41], v[32:33]
	v_pk_mul_f32 v[42:43], v[42:43], v[34:35]
	v_pk_mul_f32 v[44:45], v[44:45], v[148:149]
	v_pk_mul_f32 v[46:47], v[46:47], v[148:149]
	v_pk_mul_f32 v[40:41], v[40:41], v[148:149]
	v_pk_mul_f32 v[42:43], v[42:43], v[148:149]
	v_cvt_pk_fp8_f32 v170, v44, v45
	v_cvt_pk_fp8_f32 v171, v40, v41
	v_cvt_pk_fp8_f32 v170, v46, v47 op_sel:[0,0,1]
	v_cvt_pk_fp8_f32 v171, v42, v43 op_sel:[0,0,1]
	s_nop 0
	global_store_dwordx2 v144, v[170:171], s[22:23]
	v_add_u32_e32 v144, 0xb000, v144
	v_pk_mul_f32 v[152:153], v[28:29], v[146:147]
	v_pk_mul_f32 v[154:155], v[30:31], v[146:147]
	v_pk_mul_f32 v[156:157], v[24:25], v[146:147]
	v_pk_mul_f32 v[158:159], v[26:27], v[146:147]
	v_exp_f32_e32 v152, v152
	v_exp_f32_e32 v153, v153
	v_exp_f32_e32 v154, v154
	v_exp_f32_e32 v155, v155
	v_exp_f32_e32 v156, v156
	v_exp_f32_e32 v157, v157
	v_exp_f32_e32 v158, v158
	v_exp_f32_e32 v159, v159
	v_pk_add_f32 v[152:153], v[152:153], v[150:151]
	v_pk_add_f32 v[154:155], v[154:155], v[150:151]
	v_pk_add_f32 v[156:157], v[156:157], v[150:151]
	v_pk_add_f32 v[158:159], v[158:159], v[150:151]
	v_rcp_f32_e32 v152, v152
	v_rcp_f32_e32 v153, v153
	v_rcp_f32_e32 v154, v154
	v_rcp_f32_e32 v155, v155
	v_rcp_f32_e32 v156, v156
	v_rcp_f32_e32 v157, v157
	v_rcp_f32_e32 v158, v158
	v_rcp_f32_e32 v159, v159
	v_pk_mul_f32 v[28:29], v[28:29], v[152:153]
	v_pk_mul_f32 v[30:31], v[30:31], v[154:155]
	v_pk_mul_f32 v[24:25], v[24:25], v[156:157]
	v_pk_mul_f32 v[26:27], v[26:27], v[158:159]
	v_pk_mul_f32 v[28:29], v[28:29], v[20:21]
	v_pk_mul_f32 v[30:31], v[30:31], v[22:23]
	v_pk_mul_f32 v[24:25], v[24:25], v[16:17]
	v_pk_mul_f32 v[26:27], v[26:27], v[18:19]
	v_pk_mul_f32 v[28:29], v[28:29], v[148:149]
	v_pk_mul_f32 v[30:31], v[30:31], v[148:149]
	v_pk_mul_f32 v[24:25], v[24:25], v[148:149]
	v_pk_mul_f32 v[26:27], v[26:27], v[148:149]
	v_cvt_pk_fp8_f32 v168, v28, v29
	v_cvt_pk_fp8_f32 v169, v24, v25
	v_cvt_pk_fp8_f32 v168, v30, v31 op_sel:[0,0,1]
	v_cvt_pk_fp8_f32 v169, v26, v27 op_sel:[0,0,1]
	s_nop 0
	global_store_dwordx2 v144, v[168:169], s[22:23]
	v_add_u32_e32 v144, 0xb000, v144
	v_pk_mul_f32 v[160:161], v[12:13], v[146:147]
	v_pk_mul_f32 v[162:163], v[14:15], v[146:147]
	v_pk_mul_f32 v[164:165], v[8:9], v[146:147]
	v_pk_mul_f32 v[166:167], v[10:11], v[146:147]
	v_exp_f32_e32 v160, v160
	v_exp_f32_e32 v161, v161
	v_exp_f32_e32 v162, v162
	v_exp_f32_e32 v163, v163
	v_exp_f32_e32 v164, v164
	v_exp_f32_e32 v165, v165
	v_exp_f32_e32 v166, v166
	v_exp_f32_e32 v167, v167
	v_pk_add_f32 v[160:161], v[160:161], v[150:151]
	v_pk_add_f32 v[162:163], v[162:163], v[150:151]
	v_pk_add_f32 v[164:165], v[164:165], v[150:151]
	v_pk_add_f32 v[166:167], v[166:167], v[150:151]
	v_rcp_f32_e32 v160, v160
	v_rcp_f32_e32 v161, v161
	v_rcp_f32_e32 v162, v162
	v_rcp_f32_e32 v163, v163
	v_rcp_f32_e32 v164, v164
	v_rcp_f32_e32 v165, v165
	v_rcp_f32_e32 v166, v166
	v_rcp_f32_e32 v167, v167
	v_pk_mul_f32 v[12:13], v[12:13], v[160:161]
	v_pk_mul_f32 v[14:15], v[14:15], v[162:163]
	v_pk_mul_f32 v[8:9], v[8:9], v[164:165]
	v_pk_mul_f32 v[10:11], v[10:11], v[166:167]
	v_pk_mul_f32 v[12:13], v[12:13], v[4:5]
	v_pk_mul_f32 v[14:15], v[14:15], v[6:7]
	v_pk_mul_f32 v[8:9], v[8:9], v[0:1]
	v_pk_mul_f32 v[10:11], v[10:11], v[2:3]
	v_pk_mul_f32 v[12:13], v[12:13], v[148:149]
	v_pk_mul_f32 v[14:15], v[14:15], v[148:149]
	v_pk_mul_f32 v[8:9], v[8:9], v[148:149]
	v_pk_mul_f32 v[10:11], v[10:11], v[148:149]
	v_cvt_pk_fp8_f32 v170, v12, v13
	v_cvt_pk_fp8_f32 v171, v8, v9
	v_cvt_pk_fp8_f32 v170, v14, v15 op_sel:[0,0,1]
	v_cvt_pk_fp8_f32 v171, v10, v11 op_sel:[0,0,1]
	s_nop 0
	global_store_dwordx2 v144, v[170:171], s[22:23]
	s_cbranch_vccnz .LBB0_899
	s_andn2_b64 vcc, exec, s[20:21]
	s_cbranch_vccnz .LBB0_898
	s_barrier
	s_branch .LBB0_898

.LBB0_1509:
	s_lshl_b32 s10, s10, 1
	v_add_u32_e32 v212, s10, v249
	ds_read_b64_tr_b16 v[208:209], v212 offset:24576
	ds_read_b64_tr_b16 v[210:211], v212 offset:25088
	v_add_f32_e32 v0, v96, v97
	v_add_f32_e32 v0, v98, v0
	v_add_f32_e32 v0, v99, v0
	v_add_f32_e32 v0, v100, v0
	v_add_f32_e32 v0, v101, v0
	v_cvt_pk_bf16_f32 v156, v96, v97
	v_cvt_pk_bf16_f32 v157, v98, v99
	v_mfma_f32_32x32x16_bf16 v[112:127], v[204:207], v[172:175], 0
	ds_read_b64_tr_b16 v[204:205], v212 offset:28672
	ds_read_b64_tr_b16 v[206:207], v212 offset:29184
	v_add_f32_e32 v0, v102, v0
	v_add_f32_e32 v0, v103, v0
	v_add_f32_e32 v0, v104, v0
	v_add_f32_e32 v0, v105, v0
	v_cvt_pk_bf16_f32 v158, v100, v101
	v_cvt_pk_bf16_f32 v159, v102, v103
	v_mfma_f32_32x32x16_bf16 v[128:143], v[200:203], v[172:175], 0
	ds_read_b64_tr_b16 v[10:11], v212 offset:25600
	ds_read_b64_tr_b16 v[12:13], v212 offset:26112
	v_add_f32_e32 v0, v106, v0
	v_add_f32_e32 v0, v107, v0
	v_add_f32_e32 v0, v108, v0
	v_add_f32_e32 v0, v109, v0
	v_cvt_pk_bf16_f32 v152, v104, v105
	v_cvt_pk_bf16_f32 v153, v106, v107
	v_mfma_f32_32x32x16_bf16 v[112:127], v[196:199], v[168:171], v[112:127]
	ds_read_b64_tr_b16 v[6:7], v212 offset:29696
	ds_read_b64_tr_b16 v[8:9], v212 offset:30208
	v_add_f32_e32 v0, v110, v0
	v_add_f32_e32 v0, v111, v0
	v_add_f32_e32 v0, v80, v0
	v_add_f32_e32 v0, v81, v0
	v_cvt_pk_bf16_f32 v154, v108, v109
	v_cvt_pk_bf16_f32 v155, v110, v111
	v_mfma_f32_32x32x16_bf16 v[128:143], v[192:195], v[168:171], v[128:143]
	ds_read_b64_tr_b16 v[2:3], v212 offset:26624
	ds_read_b64_tr_b16 v[4:5], v212 offset:27136
	v_add_f32_e32 v0, v82, v0
	v_add_f32_e32 v0, v83, v0
	v_add_f32_e32 v0, v84, v0
	v_add_f32_e32 v0, v85, v0
	v_cvt_pk_bf16_f32 v148, v80, v81
	v_cvt_pk_bf16_f32 v149, v82, v83
	v_mfma_f32_32x32x16_bf16 v[112:127], v[188:191], v[164:167], v[112:127]
	ds_read_b64_tr_b16 v[188:189], v212 offset:30720
	ds_read_b64_tr_b16 v[190:191], v212 offset:31232
	v_add_f32_e32 v0, v86, v0
	v_add_f32_e32 v0, v87, v0
	v_add_f32_e32 v0, v88, v0
	v_add_f32_e32 v0, v89, v0
	v_cvt_pk_bf16_f32 v150, v84, v85
	v_cvt_pk_bf16_f32 v151, v86, v87
	v_mfma_f32_32x32x16_bf16 v[128:143], v[184:187], v[164:167], v[128:143]
	ds_read_b64_tr_b16 v[192:193], v212 offset:27648
	ds_read_b64_tr_b16 v[194:195], v212 offset:28160
	v_add_f32_e32 v0, v90, v0
	v_add_f32_e32 v0, v91, v0
	v_add_f32_e32 v0, v92, v0
	v_add_f32_e32 v0, v93, v0
	v_cvt_pk_bf16_f32 v144, v88, v89
	v_cvt_pk_bf16_f32 v145, v90, v91
	v_mfma_f32_32x32x16_bf16 v[112:127], v[180:183], v[160:163], v[112:127]
	ds_read_b64_tr_b16 v[196:197], v212 offset:31744
	ds_read_b64_tr_b16 v[198:199], v212 offset:32256
	v_add_f32_e32 v0, v94, v0
	v_add_f32_e32 v0, v95, v0
	v_add_f32_e32 v0, 0, v0
	v_cvt_pk_bf16_f32 v146, v92, v93
	v_cvt_pk_bf16_f32 v147, v94, v95
	v_mfma_f32_32x32x16_bf16 v[128:143], v[176:179], v[160:163], v[128:143]
	s_lshl_b32 s48, s47, 13
	s_add_i32 s11, s89, s66
	s_mov_b32 m0, s11
	s_add_i32 s10, s48, 0x6000
	buffer_load_dwordx4 v246, s[12:15], s10 offen lds
	s_lshl_b32 s11, s46, 1
	s_add_i32 s10, s49, 0x4000
	s_add_i32 s42, s11, s67
	s_mov_b32 m0, s42
	s_nop 0
	buffer_load_dwordx4 v247, s[16:19], s10 offen lds
	s_add_i32 s10, s49, 0x4080
	s_add_i32 s11, s11, s53
	s_mov_b32 m0, s11
	s_nop 0
	buffer_load_dwordx4 v247, s[16:19], s10 offen lds
	v_add_f32_e64 v80, v112, -v228
	v_add_f32_e64 v81, v113, -v228
	v_pk_add_f32 v[14:15], v[128:129], v[228:229] op_sel_hi:[1,0] neg_lo:[0,1] neg_hi:[0,1]
	v_pk_add_f32 v[98:99], v[114:115], v[228:229] op_sel_hi:[1,0] neg_lo:[0,1] neg_hi:[0,1]
	v_pk_add_f32 v[82:83], v[130:131], v[228:229] op_sel_hi:[1,0] neg_lo:[0,1] neg_hi:[0,1]
	v_max_f32_e32 v96, v80, v81
	v_pk_add_f32 v[100:101], v[116:117], v[228:229] op_sel_hi:[1,0] neg_lo:[0,1] neg_hi:[0,1]
	v_pk_add_f32 v[102:103], v[118:119], v[228:229] op_sel_hi:[1,0] neg_lo:[0,1] neg_hi:[0,1]
	v_max3_f32 v97, v98, v99, v15
	v_max3_f32 v96, v96, v14, v82
	v_pk_add_f32 v[84:85], v[132:133], v[228:229] op_sel_hi:[1,0] neg_lo:[0,1] neg_hi:[0,1]
	v_pk_add_f32 v[86:87], v[134:135], v[228:229] op_sel_hi:[1,0] neg_lo:[0,1] neg_hi:[0,1]
	v_max3_f32 v96, v96, v83, v100
	v_max3_f32 v97, v97, v102, v103
	v_pk_add_f32 v[104:105], v[120:121], v[228:229] op_sel_hi:[1,0] neg_lo:[0,1] neg_hi:[0,1]
	v_pk_add_f32 v[106:107], v[122:123], v[228:229] op_sel_hi:[1,0] neg_lo:[0,1] neg_hi:[0,1]
	v_max3_f32 v96, v96, v101, v84
	v_max3_f32 v97, v97, v86, v87
	v_pk_add_f32 v[88:89], v[136:137], v[228:229] op_sel_hi:[1,0] neg_lo:[0,1] neg_hi:[0,1]
	v_pk_add_f32 v[90:91], v[138:139], v[228:229] op_sel_hi:[1,0] neg_lo:[0,1] neg_hi:[0,1]
	v_max3_f32 v96, v96, v85, v104
	v_max3_f32 v97, v97, v106, v107
	v_pk_add_f32 v[108:109], v[124:125], v[228:229] op_sel_hi:[1,0] neg_lo:[0,1] neg_hi:[0,1]
	v_pk_add_f32 v[110:111], v[126:127], v[228:229] op_sel_hi:[1,0] neg_lo:[0,1] neg_hi:[0,1]
	v_max3_f32 v96, v96, v105, v88
	v_max3_f32 v97, v97, v90, v91
	v_pk_add_f32 v[92:93], v[140:141], v[228:229] op_sel_hi:[1,0] neg_lo:[0,1] neg_hi:[0,1]
	v_pk_add_f32 v[94:95], v[142:143], v[228:229] op_sel_hi:[1,0] neg_lo:[0,1] neg_hi:[0,1]
	v_max3_f32 v96, v96, v89, v108
	v_max3_f32 v97, v97, v110, v111
	v_max3_f32 v96, v96, v109, v92
	v_max3_f32 v97, v97, v94, v95
	v_max3_f32 v96, v96, v93, v97
	v_add_f32_e32 v0, v250, v0
	v_cmp_lt_f32_e32 vcc, s78, v96
	s_cmp_lg_u64 vcc, 0
	s_cselect_b64 s[10:11], -1, 0
	s_cbranch_vccnz .LBB0_1517

.LBB0_1512:
	s_add_i32 s10, s46, 0x2000
	s_cmpk_lg_i32 s46, 0x4000
	s_cselect_b32 s87, s10, 0
	s_lshl_b32 s10, s89, 1
	v_add_u32_e32 v14, s10, v249
	ds_read_b64_tr_b16 v[192:193], v14 offset:24576
	ds_read_b64_tr_b16 v[194:195], v14 offset:25088
	v_add_f32_e32 v15, v96, v97
	v_add_f32_e32 v15, v98, v15
	v_add_f32_e32 v15, v99, v15
	v_add_f32_e32 v15, v100, v15
	v_add_f32_e32 v15, v101, v15
	v_cvt_pk_bf16_f32 v156, v96, v97
	v_cvt_pk_bf16_f32 v157, v98, v99
	v_mfma_f32_32x32x16_bf16 v[112:127], v[112:115], v[172:175], 0
	ds_read_b64_tr_b16 v[196:197], v14 offset:28672
	ds_read_b64_tr_b16 v[198:199], v14 offset:29184
	v_add_f32_e32 v15, v102, v15
	v_add_f32_e32 v15, v103, v15
	v_add_f32_e32 v15, v104, v15
	v_add_f32_e32 v15, v105, v15
	v_cvt_pk_bf16_f32 v158, v100, v101
	v_cvt_pk_bf16_f32 v159, v102, v103
	v_mfma_f32_32x32x16_bf16 v[128:143], v[128:131], v[172:175], 0
	ds_read_b64_tr_b16 v[188:189], v14 offset:25600
	ds_read_b64_tr_b16 v[190:191], v14 offset:26112
	v_add_f32_e32 v15, v106, v15
	v_add_f32_e32 v15, v107, v15
	v_add_f32_e32 v15, v108, v15
	v_add_f32_e32 v15, v109, v15
	v_cvt_pk_bf16_f32 v152, v104, v105
	v_cvt_pk_bf16_f32 v153, v106, v107
	v_mfma_f32_32x32x16_bf16 v[112:127], v[184:187], v[168:171], v[112:127]
	ds_read_b64_tr_b16 v[184:185], v14 offset:29696
	ds_read_b64_tr_b16 v[186:187], v14 offset:30208
	v_add_f32_e32 v15, v110, v15
	v_add_f32_e32 v15, v111, v15
	v_add_f32_e32 v15, v80, v15
	v_add_f32_e32 v15, v81, v15
	v_cvt_pk_bf16_f32 v154, v108, v109
	v_cvt_pk_bf16_f32 v155, v110, v111
	v_mfma_f32_32x32x16_bf16 v[128:143], v[176:179], v[168:171], v[128:143]
	ds_read_b64_tr_b16 v[176:177], v14 offset:26624
	ds_read_b64_tr_b16 v[178:179], v14 offset:27136
	v_add_f32_e32 v15, v82, v15
	v_add_f32_e32 v15, v83, v15
	v_add_f32_e32 v15, v84, v15
	v_add_f32_e32 v15, v85, v15
	v_cvt_pk_bf16_f32 v148, v80, v81
	v_cvt_pk_bf16_f32 v149, v82, v83
	v_mfma_f32_32x32x16_bf16 v[112:127], v[180:183], v[164:167], v[112:127]
	ds_read_b64_tr_b16 v[208:209], v14 offset:30720
	ds_read_b64_tr_b16 v[210:211], v14 offset:31232
	v_add_f32_e32 v15, v86, v15
	v_add_f32_e32 v15, v87, v15
	v_add_f32_e32 v15, v88, v15
	v_add_f32_e32 v15, v89, v15
	v_cvt_pk_bf16_f32 v150, v84, v85
	v_cvt_pk_bf16_f32 v151, v86, v87
	v_mfma_f32_32x32x16_bf16 v[128:143], v[6:9], v[164:167], v[128:143]
	ds_read_b64_tr_b16 v[6:7], v14 offset:27648
	ds_read_b64_tr_b16 v[8:9], v14 offset:28160
	v_add_f32_e32 v15, v90, v15
	v_add_f32_e32 v15, v91, v15
	v_add_f32_e32 v15, v92, v15
	v_add_f32_e32 v15, v93, v15
	v_cvt_pk_bf16_f32 v144, v88, v89
	v_cvt_pk_bf16_f32 v145, v90, v91
	v_mfma_f32_32x32x16_bf16 v[112:127], v[10:13], v[160:163], v[112:127]
	ds_read_b64_tr_b16 v[10:11], v14 offset:31744
	ds_read_b64_tr_b16 v[12:13], v14 offset:32256
	v_add_f32_e32 v15, v94, v15
	v_add_f32_e32 v15, v95, v15
	v_add_f32_e32 v15, 0, v15
	v_cvt_pk_bf16_f32 v146, v92, v93
	v_cvt_pk_bf16_f32 v147, v94, v95
	v_mfma_f32_32x32x16_bf16 v[128:143], v[2:5], v[160:163], v[128:143]
	s_add_i32 s10, s46, s66
	s_mov_b32 m0, s10
	s_add_i32 s48, s48, 0x8000
	buffer_load_dwordx4 v246, s[12:15], s48 offen lds
	s_lshl_b32 s10, s87, 1
	s_add_i32 s89, s49, 0x8000
	s_add_i32 s11, s10, s67
	s_mov_b32 m0, s11
	s_nop 0
	buffer_load_dwordx4 v247, s[16:19], s89 offen lds
	s_add_i32 s11, s49, 0x8080
	s_add_i32 s10, s10, s53
	s_mov_b32 m0, s10
	s_nop 0
	buffer_load_dwordx4 v247, s[16:19], s11 offen lds
	v_add_f32_e64 v4, v112, -v228
	v_add_f32_e64 v5, v113, -v228
	v_pk_add_f32 v[2:3], v[128:129], v[228:229] op_sel_hi:[1,0] neg_lo:[0,1] neg_hi:[0,1]
	v_pk_add_f32 v[98:99], v[114:115], v[228:229] op_sel_hi:[1,0] neg_lo:[0,1] neg_hi:[0,1]
	v_pk_add_f32 v[82:83], v[130:131], v[228:229] op_sel_hi:[1,0] neg_lo:[0,1] neg_hi:[0,1]
	v_max_f32_e32 v80, v4, v5
	v_pk_add_f32 v[100:101], v[116:117], v[228:229] op_sel_hi:[1,0] neg_lo:[0,1] neg_hi:[0,1]
	v_pk_add_f32 v[102:103], v[118:119], v[228:229] op_sel_hi:[1,0] neg_lo:[0,1] neg_hi:[0,1]
	v_max3_f32 v81, v98, v99, v3
	v_max3_f32 v80, v80, v2, v82
	v_pk_add_f32 v[84:85], v[132:133], v[228:229] op_sel_hi:[1,0] neg_lo:[0,1] neg_hi:[0,1]
	v_pk_add_f32 v[86:87], v[134:135], v[228:229] op_sel_hi:[1,0] neg_lo:[0,1] neg_hi:[0,1]
	v_max3_f32 v80, v80, v83, v100
	v_max3_f32 v81, v81, v102, v103
	v_pk_add_f32 v[104:105], v[120:121], v[228:229] op_sel_hi:[1,0] neg_lo:[0,1] neg_hi:[0,1]
	v_pk_add_f32 v[106:107], v[122:123], v[228:229] op_sel_hi:[1,0] neg_lo:[0,1] neg_hi:[0,1]
	v_max3_f32 v80, v80, v101, v84
	v_max3_f32 v81, v81, v86, v87
	v_pk_add_f32 v[88:89], v[136:137], v[228:229] op_sel_hi:[1,0] neg_lo:[0,1] neg_hi:[0,1]
	v_pk_add_f32 v[90:91], v[138:139], v[228:229] op_sel_hi:[1,0] neg_lo:[0,1] neg_hi:[0,1]
	v_max3_f32 v80, v80, v85, v104
	v_max3_f32 v81, v81, v106, v107
	v_pk_add_f32 v[108:109], v[124:125], v[228:229] op_sel_hi:[1,0] neg_lo:[0,1] neg_hi:[0,1]
	v_pk_add_f32 v[110:111], v[126:127], v[228:229] op_sel_hi:[1,0] neg_lo:[0,1] neg_hi:[0,1]
	v_max3_f32 v80, v80, v105, v88
	v_max3_f32 v81, v81, v90, v91
	v_pk_add_f32 v[92:93], v[140:141], v[228:229] op_sel_hi:[1,0] neg_lo:[0,1] neg_hi:[0,1]
	v_pk_add_f32 v[94:95], v[142:143], v[228:229] op_sel_hi:[1,0] neg_lo:[0,1] neg_hi:[0,1]
	v_max3_f32 v80, v80, v89, v108
	v_max3_f32 v81, v81, v110, v111
	v_max3_f32 v80, v80, v109, v92
	v_max3_f32 v81, v81, v94, v95
	v_add_f32_e32 v250, v0, v15
	v_max3_f32 v0, v80, v93, v81
	v_cmp_lt_f32_e32 vcc, s78, v0
	s_cmp_lg_u64 vcc, 0
	s_cselect_b64 s[10:11], -1, 0
	s_cbranch_vccnz .LBB0_1520

.LBB0_1517:
	v_mov_b32_e32 v97, v96
	s_nop 1
	v_permlane32_swap_b32_e32 v96, v97
	v_max_f32_e32 v97, v97, v97
	v_max_f32_e32 v96, v96, v96
	v_max_f32_e32 v96, v96, v97
	v_max_f32_e32 v96, v96, v96
	v_max_f32_e32 v97, 0, v96
	v_exp_f32_e64 v96, -v97
	s_and_saveexec_b64 s[42:43], s[8:9]
	ds_write_b32 v242, v96
	s_or_b64 exec, exec, s[42:43]
	v_sub_f32_e32 v80, v80, v97
	v_sub_f32_e32 v81, v81, v97
	v_sub_f32_e32 v98, v98, v97
	v_sub_f32_e32 v99, v99, v97
	v_sub_f32_e32 v100, v100, v97
	v_sub_f32_e32 v101, v101, v97
	v_sub_f32_e32 v102, v102, v97
	v_sub_f32_e32 v103, v103, v97
	v_sub_f32_e32 v104, v104, v97
	v_sub_f32_e32 v105, v105, v97
	v_sub_f32_e32 v106, v106, v97
	v_sub_f32_e32 v107, v107, v97
	v_sub_f32_e32 v108, v108, v97
	v_sub_f32_e32 v109, v109, v97
	v_sub_f32_e32 v110, v110, v97
	v_sub_f32_e32 v111, v111, v97
	v_sub_f32_e32 v14, v14, v97
	v_sub_f32_e32 v15, v15, v97
	v_sub_f32_e32 v82, v82, v97
	v_sub_f32_e32 v83, v83, v97
	v_sub_f32_e32 v84, v84, v97
	v_sub_f32_e32 v85, v85, v97
	v_sub_f32_e32 v86, v86, v97
	v_sub_f32_e32 v87, v87, v97
	v_sub_f32_e32 v88, v88, v97
	v_sub_f32_e32 v89, v89, v97
	v_sub_f32_e32 v90, v90, v97
	v_sub_f32_e32 v91, v91, v97
	v_sub_f32_e32 v92, v92, v97
	v_sub_f32_e32 v93, v93, v97
	v_sub_f32_e32 v94, v94, v97
	v_sub_f32_e32 v95, v95, v97
	v_add_f32_e32 v228, v228, v97
	v_mul_f32_e32 v0, v0, v96
	s_branch .LBB0_1510
.LBB0_1520:
	v_mov_b32_e32 v15, v0
	s_nop 1
	v_permlane32_swap_b32_e32 v0, v15
	v_max_f32_e32 v15, v15, v15
	v_max_f32_e32 v0, v0, v0
	v_max_f32_e32 v0, v0, v15
	v_max_f32_e32 v0, v0, v0
	v_max_f32_e32 v15, 0, v0
	v_exp_f32_e64 v0, -v15
	s_and_saveexec_b64 s[42:43], s[8:9]
	ds_write_b32 v242, v0
	s_or_b64 exec, exec, s[42:43]
	v_sub_f32_e32 v4, v4, v15
	v_sub_f32_e32 v5, v5, v15
	v_sub_f32_e32 v98, v98, v15
	v_sub_f32_e32 v99, v99, v15
	v_sub_f32_e32 v100, v100, v15
	v_sub_f32_e32 v101, v101, v15
	v_sub_f32_e32 v102, v102, v15
	v_sub_f32_e32 v103, v103, v15
	v_sub_f32_e32 v104, v104, v15
	v_sub_f32_e32 v105, v105, v15
	v_sub_f32_e32 v106, v106, v15
	v_sub_f32_e32 v107, v107, v15
	v_sub_f32_e32 v108, v108, v15
	v_sub_f32_e32 v109, v109, v15
	v_sub_f32_e32 v110, v110, v15
	v_sub_f32_e32 v111, v111, v15
	v_sub_f32_e32 v2, v2, v15
	v_sub_f32_e32 v3, v3, v15
	v_sub_f32_e32 v82, v82, v15
	v_sub_f32_e32 v83, v83, v15
	v_sub_f32_e32 v84, v84, v15
	v_sub_f32_e32 v85, v85, v15
	v_sub_f32_e32 v86, v86, v15
	v_sub_f32_e32 v87, v87, v15
	v_sub_f32_e32 v88, v88, v15
	v_sub_f32_e32 v89, v89, v15
	v_sub_f32_e32 v90, v90, v15
	v_sub_f32_e32 v91, v91, v15
	v_sub_f32_e32 v92, v92, v15
	v_sub_f32_e32 v93, v93, v15
	v_sub_f32_e32 v94, v94, v15
	v_sub_f32_e32 v95, v95, v15
	v_add_f32_e32 v228, v228, v15
	v_mul_f32_e32 v250, v250, v0
	s_branch .LBB0_1513

; __device__ __forceinline__ float sigm(float x) { return __builtin_amdgcn_rcpf(1.f + __builtin_amdgcn_exp2f(-1.4426950408889634f * x)); }
;     __device__ __forceinline__ void operator()(const f32x4 (&acc)[2][2][4][2], const Unit& u, int wr, int wc, int fr, int fq) const {
;         const int pnl = u.pn % nper; const int row0 = u.pm * BM + wr * 64 + fr, col0 = pnl * HALF + wc * 32 + 8 * fq;
; #pragma unroll
;         for (int ai = 0; ai < 2; ++ai)
; #pragma unroll
;             for (int m = 0; m < 4; ++m) { const f32x4 g0 = acc[ai][0][m][0] * isc, g1 = acc[ai][0][m][1] * isc, u0 = acc[ai][1][m][0] * isc, u1 = acc[ai][1][m][1] * isc; float r[8];
; #pragma unroll
;                 for (int i = 0; i < 4; ++i) { r[i] = g0[i] * sigm(g0[i]) * u0[i] * osc; r[4 + i] = g1[i] * sigm(g1[i]) * u1[i] * osc; }
;                 int w0 = 0, w1 = 0; w0 = __builtin_amdgcn_cvt_pk_fp8_f32(r[0], r[1], w0, false); w0 = __builtin_amdgcn_cvt_pk_fp8_f32(r[2], r[3], w0, true);
;                 w1 = __builtin_amdgcn_cvt_pk_fp8_f32(r[4], r[5], w1, false); w1 = __builtin_amdgcn_cvt_pk_fp8_f32(r[6], r[7], w1, true);
;                 typedef unsigned u32x2 __attribute__((ext_vector_type(2)));
;                 *(u32x2*)(O + (size_t)(row0 + ai * HALF + m * 16) * ldo + col0) = (u32x2){(unsigned)w0, (unsigned)w1}; }
;     }
.LBB0_2102:
	s_mul_hi_i32 s14, s60, 0x92492493
	s_add_i32 s14, s14, s60
	s_lshr_b32 s15, s14, 31
	s_lshr_b32 s14, s14, 4
	s_add_i32 s14, s14, s15
	s_mul_i32 s14, s14, 28
	s_sub_i32 s14, s60, s14
	s_lshl_b32 s14, s14, 7
	s_lshl_b32 s15, s26, 8
	s_add_i32 s15, s15, s71
	v_mbcnt_lo_u32_b32 v145, -1, 0
	v_mbcnt_hi_u32_b32 v145, -1, v145
	v_mov_b32_e32 v146, 0xbcb8aa3b
	v_and_or_b32 v143, v145, 15, s15
	v_lshrrev_b32_e32 v145, 1, v145
	v_mov_b32_e32 v147, 0xbcb8aa3b
	v_and_or_b32 v145, v145, 24, s14
	v_or_b32_e32 v145, s75, v145
	v_mov_b32_e32 v148, 0x3b800000
	v_mov_b32_e32 v149, 0x3b800000
	v_mad_u32_u24 v144, v143, s57, v145
	v_mov_b32_e32 v150, 1.0
	v_mov_b32_e32 v151, 1.0
	s_andn2_b64 vcc, exec, s[6:7]
	s_mov_b64 s[6:7], -1
	v_pk_mul_f32 v[152:153], v[124:125], v[146:147]
	v_pk_mul_f32 v[154:155], v[126:127], v[146:147]
	v_pk_mul_f32 v[156:157], v[120:121], v[146:147]
	v_pk_mul_f32 v[158:159], v[122:123], v[146:147]
	v_exp_f32_e32 v152, v152
	v_exp_f32_e32 v153, v153
	v_exp_f32_e32 v154, v154
	v_exp_f32_e32 v155, v155
	v_exp_f32_e32 v156, v156
	v_exp_f32_e32 v157, v157
	v_exp_f32_e32 v158, v158
	v_exp_f32_e32 v159, v159
	v_pk_add_f32 v[152:153], v[152:153], v[150:151]
	v_pk_add_f32 v[154:155], v[154:155], v[150:151]
	v_pk_add_f32 v[156:157], v[156:157], v[150:151]
	v_pk_add_f32 v[158:159], v[158:159], v[150:151]
	v_rcp_f32_e32 v152, v152
	v_rcp_f32_e32 v153, v153
	v_rcp_f32_e32 v154, v154
	v_rcp_f32_e32 v155, v155
	v_rcp_f32_e32 v156, v156
	v_rcp_f32_e32 v157, v157
	v_rcp_f32_e32 v158, v158
	v_rcp_f32_e32 v159, v159
	v_pk_mul_f32 v[124:125], v[124:125], v[152:153]
	v_pk_mul_f32 v[126:127], v[126:127], v[154:155]
	v_pk_mul_f32 v[120:121], v[120:121], v[156:157]
	v_pk_mul_f32 v[122:123], v[122:123], v[158:159]
	v_pk_mul_f32 v[124:125], v[124:125], v[116:117]
	v_pk_mul_f32 v[126:127], v[126:127], v[118:119]
	v_pk_mul_f32 v[120:121], v[120:121], v[112:113]
	v_pk_mul_f32 v[122:123], v[122:123], v[114:115]
	v_pk_mul_f32 v[124:125], v[124:125], v[148:149]
	v_pk_mul_f32 v[126:127], v[126:127], v[148:149]
	v_pk_mul_f32 v[120:121], v[120:121], v[148:149]
	v_pk_mul_f32 v[122:123], v[122:123], v[148:149]
	v_cvt_pk_fp8_f32 v168, v124, v125
	v_cvt_pk_fp8_f32 v169, v120, v121
	v_cvt_pk_fp8_f32 v168, v126, v127 op_sel:[0,0,1]
	v_cvt_pk_fp8_f32 v169, v122, v123 op_sel:[0,0,1]
	s_nop 0
	global_store_dwordx2 v144, v[168:169], s[18:19]
	v_add_u32_e32 v144, 0xe000, v144
	v_pk_mul_f32 v[160:161], v[108:109], v[146:147]
	v_pk_mul_f32 v[162:163], v[110:111], v[146:147]
	v_pk_mul_f32 v[164:165], v[104:105], v[146:147]
	v_pk_mul_f32 v[166:167], v[106:107], v[146:147]
	v_exp_f32_e32 v160, v160
	v_exp_f32_e32 v161, v161
	v_exp_f32_e32 v162, v162
	v_exp_f32_e32 v163, v163
	v_exp_f32_e32 v164, v164
	v_exp_f32_e32 v165, v165
	v_exp_f32_e32 v166, v166
	v_exp_f32_e32 v167, v167
	v_pk_add_f32 v[160:161], v[160:161], v[150:151]
	v_pk_add_f32 v[162:163], v[162:163], v[150:151]
	v_pk_add_f32 v[164:165], v[164:165], v[150:151]
	v_pk_add_f32 v[166:167], v[166:167], v[150:151]
	v_rcp_f32_e32 v160, v160
	v_rcp_f32_e32 v161, v161
	v_rcp_f32_e32 v162, v162
	v_rcp_f32_e32 v163, v163
	v_rcp_f32_e32 v164, v164
	v_rcp_f32_e32 v165, v165
	v_rcp_f32_e32 v166, v166
	v_rcp_f32_e32 v167, v167
	v_pk_mul_f32 v[108:109], v[108:109], v[160:161]
	v_pk_mul_f32 v[110:111], v[110:111], v[162:163]
	v_pk_mul_f32 v[104:105], v[104:105], v[164:165]
	v_pk_mul_f32 v[106:107], v[106:107], v[166:167]
	v_pk_mul_f32 v[108:109], v[108:109], v[100:101]
	v_pk_mul_f32 v[110:111], v[110:111], v[102:103]
	v_pk_mul_f32 v[104:105], v[104:105], v[96:97]
	v_pk_mul_f32 v[106:107], v[106:107], v[98:99]
	v_pk_mul_f32 v[108:109], v[108:109], v[148:149]
	v_pk_mul_f32 v[110:111], v[110:111], v[148:149]
	v_pk_mul_f32 v[104:105], v[104:105], v[148:149]
	v_pk_mul_f32 v[106:107], v[106:107], v[148:149]
	v_cvt_pk_fp8_f32 v170, v108, v109
	v_cvt_pk_fp8_f32 v171, v104, v105
	v_cvt_pk_fp8_f32 v170, v110, v111 op_sel:[0,0,1]
	v_cvt_pk_fp8_f32 v171, v106, v107 op_sel:[0,0,1]
	s_nop 0
	global_store_dwordx2 v144, v[170:171], s[18:19]
	v_add_u32_e32 v144, 0xe000, v144
	v_pk_mul_f32 v[152:153], v[92:93], v[146:147]
	v_pk_mul_f32 v[154:155], v[94:95], v[146:147]
	v_pk_mul_f32 v[156:157], v[88:89], v[146:147]
	v_pk_mul_f32 v[158:159], v[90:91], v[146:147]
	v_exp_f32_e32 v152, v152
	v_exp_f32_e32 v153, v153
	v_exp_f32_e32 v154, v154
	v_exp_f32_e32 v155, v155
	v_exp_f32_e32 v156, v156
	v_exp_f32_e32 v157, v157
	v_exp_f32_e32 v158, v158
	v_exp_f32_e32 v159, v159
	v_pk_add_f32 v[152:153], v[152:153], v[150:151]
	v_pk_add_f32 v[154:155], v[154:155], v[150:151]
	v_pk_add_f32 v[156:157], v[156:157], v[150:151]
	v_pk_add_f32 v[158:159], v[158:159], v[150:151]
	v_rcp_f32_e32 v152, v152
	v_rcp_f32_e32 v153, v153
	v_rcp_f32_e32 v154, v154
	v_rcp_f32_e32 v155, v155
	v_rcp_f32_e32 v156, v156
	v_rcp_f32_e32 v157, v157
	v_rcp_f32_e32 v158, v158
	v_rcp_f32_e32 v159, v159
	v_pk_mul_f32 v[92:93], v[92:93], v[152:153]
	v_pk_mul_f32 v[94:95], v[94:95], v[154:155]
	v_pk_mul_f32 v[88:89], v[88:89], v[156:157]
	v_pk_mul_f32 v[90:91], v[90:91], v[158:159]
	v_pk_mul_f32 v[92:93], v[92:93], v[84:85]
	v_pk_mul_f32 v[94:95], v[94:95], v[86:87]
	v_pk_mul_f32 v[88:89], v[88:89], v[80:81]
	v_pk_mul_f32 v[90:91], v[90:91], v[82:83]
	v_pk_mul_f32 v[92:93], v[92:93], v[148:149]
	v_pk_mul_f32 v[94:95], v[94:95], v[148:149]
	v_pk_mul_f32 v[88:89], v[88:89], v[148:149]
	v_pk_mul_f32 v[90:91], v[90:91], v[148:149]
	v_cvt_pk_fp8_f32 v168, v92, v93
	v_cvt_pk_fp8_f32 v169, v88, v89
	v_cvt_pk_fp8_f32 v168, v94, v95 op_sel:[0,0,1]
	v_cvt_pk_fp8_f32 v169, v90, v91 op_sel:[0,0,1]
	s_nop 0
	global_store_dwordx2 v144, v[168:169], s[18:19]
	v_add_u32_e32 v144, 0xe000, v144
; __device__ __forceinline__ float sigm(float x) { return __builtin_amdgcn_rcpf(1.f + __builtin_amdgcn_exp2f(-1.4426950408889634f * x)); }
;     __device__ __forceinline__ void operator()(const f32x4 (&acc)[2][2][4][2], const Unit& u, int wr, int wc, int fr, int fq) const {
;     ...
;         for (int ai = 0; ai < 2; ++ai)
; #pragma unroll
;             for (int m = 0; m < 4; ++m) { const f32x4 g0 = acc[ai][0][m][0] * isc, g1 = acc[ai][0][m][1] * isc, u0 = acc[ai][1][m][0] * isc, u1 = acc[ai][1][m][1] * isc; float r[8];
; #pragma unroll
;                 for (int i = 0; i < 4; ++i) { r[i] = g0[i] * sigm(g0[i]) * u0[i] * osc; r[4 + i] = g1[i] * sigm(g1[i]) * u1[i] * osc; }
;                 int w0 = 0, w1 = 0; w0 = __builtin_amdgcn_cvt_pk_fp8_f32(r[0], r[1], w0, false); w0 = __builtin_amdgcn_cvt_pk_fp8_f32(r[2], r[3], w0, true);
;                 w1 = __builtin_amdgcn_cvt_pk_fp8_f32(r[4], r[5], w1, false); w1 = __builtin_amdgcn_cvt_pk_fp8_f32(r[6], r[7], w1, true);
;                 typedef unsigned u32x2 __attribute__((ext_vector_type(2)));
;                 *(u32x2*)(O + (size_t)(row0 + ai * HALF + m * 16) * ldo + col0) = (u32x2){(unsigned)w0, (unsigned)w1}; }
	v_pk_mul_f32 v[160:161], v[76:77], v[146:147]
	v_pk_mul_f32 v[162:163], v[78:79], v[146:147]
	v_pk_mul_f32 v[164:165], v[72:73], v[146:147]
	v_pk_mul_f32 v[166:167], v[74:75], v[146:147]
	v_exp_f32_e32 v160, v160
	v_exp_f32_e32 v161, v161
	v_exp_f32_e32 v162, v162
	v_exp_f32_e32 v163, v163
	v_exp_f32_e32 v164, v164
	v_exp_f32_e32 v165, v165
	v_exp_f32_e32 v166, v166
	v_exp_f32_e32 v167, v167
	v_pk_add_f32 v[160:161], v[160:161], v[150:151]
	v_pk_add_f32 v[162:163], v[162:163], v[150:151]
	v_pk_add_f32 v[164:165], v[164:165], v[150:151]
	v_pk_add_f32 v[166:167], v[166:167], v[150:151]
	v_rcp_f32_e32 v160, v160
	v_rcp_f32_e32 v161, v161
	v_rcp_f32_e32 v162, v162
	v_rcp_f32_e32 v163, v163
	v_rcp_f32_e32 v164, v164
	v_rcp_f32_e32 v165, v165
	v_rcp_f32_e32 v166, v166
	v_rcp_f32_e32 v167, v167
	v_pk_mul_f32 v[76:77], v[76:77], v[160:161]
	v_pk_mul_f32 v[78:79], v[78:79], v[162:163]
	v_pk_mul_f32 v[72:73], v[72:73], v[164:165]
	v_pk_mul_f32 v[74:75], v[74:75], v[166:167]
	v_pk_mul_f32 v[76:77], v[76:77], v[68:69]
	v_pk_mul_f32 v[78:79], v[78:79], v[70:71]
	v_pk_mul_f32 v[72:73], v[72:73], v[64:65]
	v_pk_mul_f32 v[74:75], v[74:75], v[66:67]
	v_pk_mul_f32 v[76:77], v[76:77], v[148:149]
	v_pk_mul_f32 v[78:79], v[78:79], v[148:149]
	v_pk_mul_f32 v[72:73], v[72:73], v[148:149]
	v_pk_mul_f32 v[74:75], v[74:75], v[148:149]
	v_cvt_pk_fp8_f32 v170, v76, v77
	v_cvt_pk_fp8_f32 v171, v72, v73
	v_cvt_pk_fp8_f32 v170, v78, v79 op_sel:[0,0,1]
	v_cvt_pk_fp8_f32 v171, v74, v75 op_sel:[0,0,1]
	s_nop 0
	global_store_dwordx2 v144, v[170:171], s[18:19]
	v_add_u32_e32 v144, 0x46000, v144
	v_pk_mul_f32 v[152:153], v[60:61], v[146:147]
	v_pk_mul_f32 v[154:155], v[62:63], v[146:147]
	v_pk_mul_f32 v[156:157], v[56:57], v[146:147]
	v_pk_mul_f32 v[158:159], v[58:59], v[146:147]
	v_exp_f32_e32 v152, v152
	v_exp_f32_e32 v153, v153
	v_exp_f32_e32 v154, v154
	v_exp_f32_e32 v155, v155
	v_exp_f32_e32 v156, v156
	v_exp_f32_e32 v157, v157
	v_exp_f32_e32 v158, v158
	v_exp_f32_e32 v159, v159
	v_pk_add_f32 v[152:153], v[152:153], v[150:151]
	v_pk_add_f32 v[154:155], v[154:155], v[150:151]
	v_pk_add_f32 v[156:157], v[156:157], v[150:151]
	v_pk_add_f32 v[158:159], v[158:159], v[150:151]
	v_rcp_f32_e32 v152, v152
	v_rcp_f32_e32 v153, v153
	v_rcp_f32_e32 v154, v154
	v_rcp_f32_e32 v155, v155
	v_rcp_f32_e32 v156, v156
	v_rcp_f32_e32 v157, v157
	v_rcp_f32_e32 v158, v158
	v_rcp_f32_e32 v159, v159
	v_pk_mul_f32 v[60:61], v[60:61], v[152:153]
	v_pk_mul_f32 v[62:63], v[62:63], v[154:155]
	v_pk_mul_f32 v[56:57], v[56:57], v[156:157]
	v_pk_mul_f32 v[58:59], v[58:59], v[158:159]
	v_pk_mul_f32 v[60:61], v[60:61], v[52:53]
	v_pk_mul_f32 v[62:63], v[62:63], v[54:55]
	v_pk_mul_f32 v[56:57], v[56:57], v[48:49]
	v_pk_mul_f32 v[58:59], v[58:59], v[50:51]
	v_pk_mul_f32 v[60:61], v[60:61], v[148:149]
	v_pk_mul_f32 v[62:63], v[62:63], v[148:149]
	v_pk_mul_f32 v[56:57], v[56:57], v[148:149]
	v_pk_mul_f32 v[58:59], v[58:59], v[148:149]
	v_cvt_pk_fp8_f32 v168, v60, v61
	v_cvt_pk_fp8_f32 v169, v56, v57
	v_cvt_pk_fp8_f32 v168, v62, v63 op_sel:[0,0,1]
	v_cvt_pk_fp8_f32 v169, v58, v59 op_sel:[0,0,1]
	s_nop 0
	global_store_dwordx2 v144, v[168:169], s[18:19]
	v_add_u32_e32 v144, 0xe000, v144
	v_pk_mul_f32 v[160:161], v[44:45], v[146:147]
	v_pk_mul_f32 v[162:163], v[46:47], v[146:147]
	v_pk_mul_f32 v[164:165], v[40:41], v[146:147]
	v_pk_mul_f32 v[166:167], v[42:43], v[146:147]
	v_exp_f32_e32 v160, v160
	v_exp_f32_e32 v161, v161
	v_exp_f32_e32 v162, v162
	v_exp_f32_e32 v163, v163
	v_exp_f32_e32 v164, v164
	v_exp_f32_e32 v165, v165
	v_exp_f32_e32 v166, v166
	v_exp_f32_e32 v167, v167
	v_pk_add_f32 v[160:161], v[160:161], v[150:151]
	v_pk_add_f32 v[162:163], v[162:163], v[150:151]
	v_pk_add_f32 v[164:165], v[164:165], v[150:151]
	v_pk_add_f32 v[166:167], v[166:167], v[150:151]
	v_rcp_f32_e32 v160, v160
	v_rcp_f32_e32 v161, v161
	v_rcp_f32_e32 v162, v162
	v_rcp_f32_e32 v163, v163
	v_rcp_f32_e32 v164, v164
	v_rcp_f32_e32 v165, v165
	v_rcp_f32_e32 v166, v166
	v_rcp_f32_e32 v167, v167
	v_pk_mul_f32 v[44:45], v[44:45], v[160:161]
; __device__ __forceinline__ float sigm(float x) { return __builtin_amdgcn_rcpf(1.f + __builtin_amdgcn_exp2f(-1.4426950408889634f * x)); }
;     __device__ __forceinline__ void operator()(const f32x4 (&acc)[2][2][4][2], const Unit& u, int wr, int wc, int fr, int fq) const {
;     ...
;         for (int ai = 0; ai < 2; ++ai)
; #pragma unroll
;             for (int m = 0; m < 4; ++m) { const f32x4 g0 = acc[ai][0][m][0] * isc, g1 = acc[ai][0][m][1] * isc, u0 = acc[ai][1][m][0] * isc, u1 = acc[ai][1][m][1] * isc; float r[8];
; #pragma unroll
;                 for (int i = 0; i < 4; ++i) { r[i] = g0[i] * sigm(g0[i]) * u0[i] * osc; r[4 + i] = g1[i] * sigm(g1[i]) * u1[i] * osc; }
;                 int w0 = 0, w1 = 0; w0 = __builtin_amdgcn_cvt_pk_fp8_f32(r[0], r[1], w0, false); w0 = __builtin_amdgcn_cvt_pk_fp8_f32(r[2], r[3], w0, true);
;                 w1 = __builtin_amdgcn_cvt_pk_fp8_f32(r[4], r[5], w1, false); w1 = __builtin_amdgcn_cvt_pk_fp8_f32(r[6], r[7], w1, true);
;                 typedef unsigned u32x2 __attribute__((ext_vector_type(2)));
;                 *(u32x2*)(O + (size_t)(row0 + ai * HALF + m * 16) * ldo + col0) = (u32x2){(unsigned)w0, (unsigned)w1}; }
	v_pk_mul_f32 v[46:47], v[46:47], v[162:163]
	v_pk_mul_f32 v[40:41], v[40:41], v[164:165]
	v_pk_mul_f32 v[42:43], v[42:43], v[166:167]
	v_pk_mul_f32 v[44:45], v[44:45], v[36:37]
	v_pk_mul_f32 v[46:47], v[46:47], v[38:39]
	v_pk_mul_f32 v[40:41], v[40:41], v[32:33]
	v_pk_mul_f32 v[42:43], v[42:43], v[34:35]
	v_pk_mul_f32 v[44:45], v[44:45], v[148:149]
	v_pk_mul_f32 v[46:47], v[46:47], v[148:149]
	v_pk_mul_f32 v[40:41], v[40:41], v[148:149]
	v_pk_mul_f32 v[42:43], v[42:43], v[148:149]
	v_cvt_pk_fp8_f32 v170, v44, v45
	v_cvt_pk_fp8_f32 v171, v40, v41
	v_cvt_pk_fp8_f32 v170, v46, v47 op_sel:[0,0,1]
	v_cvt_pk_fp8_f32 v171, v42, v43 op_sel:[0,0,1]
	s_nop 0
	global_store_dwordx2 v144, v[170:171], s[18:19]
	v_add_u32_e32 v144, 0xe000, v144
	v_pk_mul_f32 v[152:153], v[28:29], v[146:147]
	v_pk_mul_f32 v[154:155], v[30:31], v[146:147]
	v_pk_mul_f32 v[156:157], v[24:25], v[146:147]
	v_pk_mul_f32 v[158:159], v[26:27], v[146:147]
	v_exp_f32_e32 v152, v152
	v_exp_f32_e32 v153, v153
	v_exp_f32_e32 v154, v154
	v_exp_f32_e32 v155, v155
	v_exp_f32_e32 v156, v156
	v_exp_f32_e32 v157, v157
	v_exp_f32_e32 v158, v158
	v_exp_f32_e32 v159, v159
	v_pk_add_f32 v[152:153], v[152:153], v[150:151]
	v_pk_add_f32 v[154:155], v[154:155], v[150:151]
	v_pk_add_f32 v[156:157], v[156:157], v[150:151]
	v_pk_add_f32 v[158:159], v[158:159], v[150:151]
	v_rcp_f32_e32 v152, v152
	v_rcp_f32_e32 v153, v153
	v_rcp_f32_e32 v154, v154
	v_rcp_f32_e32 v155, v155
	v_rcp_f32_e32 v156, v156
	v_rcp_f32_e32 v157, v157
	v_rcp_f32_e32 v158, v158
	v_rcp_f32_e32 v159, v159
	v_pk_mul_f32 v[28:29], v[28:29], v[152:153]
	v_pk_mul_f32 v[30:31], v[30:31], v[154:155]
	v_pk_mul_f32 v[24:25], v[24:25], v[156:157]
	v_pk_mul_f32 v[26:27], v[26:27], v[158:159]
	v_pk_mul_f32 v[28:29], v[28:29], v[20:21]
	v_pk_mul_f32 v[30:31], v[30:31], v[22:23]
	v_pk_mul_f32 v[24:25], v[24:25], v[16:17]
	v_pk_mul_f32 v[26:27], v[26:27], v[18:19]
	v_pk_mul_f32 v[28:29], v[28:29], v[148:149]
	v_pk_mul_f32 v[30:31], v[30:31], v[148:149]
	v_pk_mul_f32 v[24:25], v[24:25], v[148:149]
	v_pk_mul_f32 v[26:27], v[26:27], v[148:149]
	v_cvt_pk_fp8_f32 v168, v28, v29
	v_cvt_pk_fp8_f32 v169, v24, v25
	v_cvt_pk_fp8_f32 v168, v30, v31 op_sel:[0,0,1]
	v_cvt_pk_fp8_f32 v169, v26, v27 op_sel:[0,0,1]
	s_nop 0
	global_store_dwordx2 v144, v[168:169], s[18:19]
	v_add_u32_e32 v144, 0xe000, v144
	v_pk_mul_f32 v[160:161], v[12:13], v[146:147]
	v_pk_mul_f32 v[162:163], v[14:15], v[146:147]
	v_pk_mul_f32 v[164:165], v[8:9], v[146:147]
	v_pk_mul_f32 v[166:167], v[10:11], v[146:147]
	v_exp_f32_e32 v160, v160
	v_exp_f32_e32 v161, v161
	v_exp_f32_e32 v162, v162
	v_exp_f32_e32 v163, v163
	v_exp_f32_e32 v164, v164
	v_exp_f32_e32 v165, v165
	v_exp_f32_e32 v166, v166
	v_exp_f32_e32 v167, v167
	v_pk_add_f32 v[160:161], v[160:161], v[150:151]
	v_pk_add_f32 v[162:163], v[162:163], v[150:151]
	v_pk_add_f32 v[164:165], v[164:165], v[150:151]
	v_pk_add_f32 v[166:167], v[166:167], v[150:151]
	v_rcp_f32_e32 v160, v160
	v_rcp_f32_e32 v161, v161
	v_rcp_f32_e32 v162, v162
	v_rcp_f32_e32 v163, v163
	v_rcp_f32_e32 v164, v164
	v_rcp_f32_e32 v165, v165
	v_rcp_f32_e32 v166, v166
	v_rcp_f32_e32 v167, v167
	v_pk_mul_f32 v[12:13], v[12:13], v[160:161]
	v_pk_mul_f32 v[14:15], v[14:15], v[162:163]
	v_pk_mul_f32 v[8:9], v[8:9], v[164:165]
	v_pk_mul_f32 v[10:11], v[10:11], v[166:167]
	v_pk_mul_f32 v[12:13], v[12:13], v[4:5]
	v_pk_mul_f32 v[14:15], v[14:15], v[6:7]
	v_pk_mul_f32 v[8:9], v[8:9], v[0:1]
	v_pk_mul_f32 v[10:11], v[10:11], v[2:3]
	v_pk_mul_f32 v[12:13], v[12:13], v[148:149]
	v_pk_mul_f32 v[14:15], v[14:15], v[148:149]
	v_pk_mul_f32 v[8:9], v[8:9], v[148:149]
	v_pk_mul_f32 v[10:11], v[10:11], v[148:149]
	v_cvt_pk_fp8_f32 v170, v12, v13
	v_cvt_pk_fp8_f32 v171, v8, v9
	v_cvt_pk_fp8_f32 v170, v14, v15 op_sel:[0,0,1]
	v_cvt_pk_fp8_f32 v171, v10, v11 op_sel:[0,0,1]
	s_nop 0
	global_store_dwordx2 v144, v[170:171], s[18:19]
	s_cbranch_vccnz .LBB0_2091
	s_andn2_b64 vcc, exec, s[16:17]
	s_cbranch_vccnz .LBB0_2090
	s_barrier
	s_branch .LBB0_2090
